# attention first key tile (16 real meta keys): the three PV chunks whose P operand is exp2(-inf)=0 removed (12 MFMAs + 12 serialized LDS reads per unit, they add exactly zero)
# speedup vs baseline: 1.0025x; 1.0011x over previous
; __device__ __forceinline__ int pi32(int r) { return (r & 0x13) | ((r & 4) << 1) | ((r & 8) >> 1); }
; __device__ __forceinline__ void attn_unit(LAS unsigned char* lds, const bf16_t* Q, const bf16_t* KN, const bf16_t* KPE, const bf16_t* VT, bf16_t* Y, float* ssq_b, int b, int h, int qg) {
;     const int tid = threadIdx.x, wid = __builtin_amdgcn_readfirstlane(tid >> 6), lane = tid & 63, q = lane & 31, hh = lane >> 5;
;     const int t0 = 16 + 256 * qg, c0 = 1 + 4 * qg, cw = c0 + (wid >> 1), ntiles = c0 + 4;
;     bf16x8 qf[12];
;     {
;         const bf16_t* qp = Q + (size_t)(b * 2048 + (t0 - 16) + 32 * wid + q) * 1536 + h * 192 + 8 * hh;
; #pragma unroll
;         for (int ks = 0; ks < 12; ++ks) qf[ks] = *(const bf16x8*)(qp + 16 * ks);
;     }
;     f32x16 o[4];
; #pragma unroll
;     for (int d = 0; d < 4; ++d)
; #pragma unroll
;         for (int i = 0; i < 16; ++i) o[d][i] = 0.f;
;     float mrun = -INFINITY, lsum = 0.f;
;     const char* ksrc[3]; unsigned kstr[3]; const char* vsrc[2];
; #pragma unroll
;     for (int i = 0; i < 3; ++i) {
;         const int s = 64 * (wid * 3 + i) + lane; const int key = s / 24, pos = s - key * 24; const int pc = pos ^ ((key >> 1) & 7);
;         const size_t row = (size_t)b * 2048 + key;
;         if (pc < 16) { ksrc[i] = (const char*)(KN + row * 1024 + h * 128 + pc * 8); kstr[i] = 2048u; }
;         else { ksrc[i] = (const char*)(KPE + row * 64 + (pc - 16) * 8); kstr[i] = 128u; }
;     }
; #pragma unroll
;     for (int i = 0; i < 2; ++i) {
;         const int s = 64 * (wid * 2 + i) + lane; const int d = s >> 3, pos = s & 7; const int pc = pos ^ ((d >> 1) & 7);
;         vsrc[i] = (const char*)(VT + ((size_t)((b * 8 + h) * 128 + d)) * 2048 + pc * 8);
;     }
;     ...
;     const int key0 = pi32(q);
;     const unsigned kbase0 = (unsigned)(key0 * 384) + (unsigned)(((hh ^ ((key0 >> 1) & 7))) << 4);
;     const unsigned vbase0 = (unsigned)(q * 128) + (unsigned)((hh ^ ((q >> 1) & 7)) << 4);
;     AT_DMA(0); __syncthreads();
.LBB0_652:
	s_lshl_b32 s6, s39, 3
	s_and_b32 s6, s6, 56
	s_ashr_i32 s7, s39, 5
	s_add_i32 s6, s6, s7
	s_bfe_u32 s45, s39, 0x20003
	s_ashr_i32 s8, s6, 3
	s_xor_b32 s52, s45, 7
	v_readfirstlane_b32 s53, v170
	s_lshl_b32 s13, s8, 11
	s_lshr_b32 s56, s53, 6
	s_lshl_b32 s28, s52, 8
	v_or_b32_e32 v211, s13, v149
	s_lshl_b32 s12, s56, 5
	v_or_b32_e32 v0, s28, v211
	v_add_u32_e32 v2, s12, v0
	s_waitcnt lgkmcnt(0)
	v_mov_b64_e32 v[0:1], s[60:61]
	s_and_b32 s29, s7, 7
	v_mad_i64_i32 v[0:1], s[6:7], v2, s31, v[0:1]
	s_mul_i32 s6, s29, 0xc0
	s_lshl_b32 s16, s6, 1
	v_lshl_add_u64 v[0:1], v[0:1], 0, s[16:17]
	v_mov_b32_e32 v157, v151
	v_lshl_add_u64 v[0:1], v[0:1], 0, v[156:157]
	global_load_dwordx4 v[140:143], v[0:1], off
	global_load_dwordx4 v[136:139], v[0:1], off offset:32
	global_load_dwordx4 v[132:135], v[0:1], off offset:64
	global_load_dwordx4 v[128:131], v[0:1], off offset:96
	global_load_dwordx4 v[124:127], v[0:1], off offset:128
	global_load_dwordx4 v[120:123], v[0:1], off offset:160
	global_load_dwordx4 v[116:119], v[0:1], off offset:192
	global_load_dwordx4 v[112:115], v[0:1], off offset:224
	global_load_dwordx4 v[108:111], v[0:1], off offset:256
	global_load_dwordx4 v[104:107], v[0:1], off offset:288
	global_load_dwordx4 v[100:103], v[0:1], off offset:320
	global_load_dwordx4 v[96:99], v[0:1], off offset:352
	s_ashr_i32 s9, s8, 31
	s_lshl_b64 s[24:25], s[8:9], 11
	s_mul_i32 s9, s56, 0xc0
	v_or_b32_e32 v0, s9, v144
	v_mul_hi_u32 v2, v0, s34
	v_lshrrev_b32_e32 v150, 4, v2
	v_mad_u64_u32 v[0:1], s[10:11], v150, s35, v[0:1]
	s_lshl_b32 s6, s29, 8
	v_lshrrev_b32_e32 v1, 5, v2
	s_add_u32 s6, s4, s6
	v_bitop3_b32 v0, v0, v1, 7 bitop3:0x78
	s_addc_u32 s7, s5, 0
	v_lshl_add_u64 v[2:3], s[24:25], 0, v[150:151]
	v_cmp_lt_i32_e32 vcc, 15, v0
	v_lshlrev_b32_e32 v0, 3, v0
	s_and_saveexec_b64 s[10:11], vcc
	s_xor_b64 s[10:11], exec, s[10:11]
	v_lshlrev_b64 v[2:3], 7, v[2:3]
	v_lshl_add_u64 v[2:3], s[14:15], 0, v[2:3]
	v_add_u32_e32 v150, 0xffffff80, v0
	v_lshl_add_u64 v[160:161], v[150:151], 1, v[2:3]
	s_or_saveexec_b64 s[10:11], s[10:11]
	v_mov_b64_e32 v[162:163], 0x80
	s_xor_b64 exec, exec, s[10:11]
	v_lshlrev_b64 v[2:3], 11, v[2:3]
	v_lshl_add_u64 v[2:3], s[6:7], 0, v[2:3]
	v_ashrrev_i32_e32 v1, 31, v0
	v_lshl_add_u64 v[160:161], v[0:1], 1, v[2:3]
	v_mov_b64_e32 v[162:163], 0x800
	s_or_b64 exec, exec, s[10:11]
	s_mul_i32 s64, s56, 3
	s_add_i32 s57, s64, 1
	v_lshl_or_b32 v0, s57, 6, v144
	v_mul_hi_u32 v2, v0, s36
	v_lshrrev_b32_e32 v150, 2, v2
	v_mad_u64_u32 v[0:1], s[10:11], v150, s35, v[0:1]
	v_lshrrev_b32_e32 v1, 3, v2
	v_bitop3_b32 v0, v0, v1, 7 bitop3:0x78
	v_lshl_add_u64 v[2:3], s[24:25], 0, v[150:151]
	v_cmp_lt_i32_e32 vcc, 15, v0
	v_lshlrev_b32_e32 v0, 3, v0
	s_and_saveexec_b64 s[10:11], vcc
	s_xor_b64 s[10:11], exec, s[10:11]
	v_lshlrev_b64 v[2:3], 7, v[2:3]
	v_lshl_add_u64 v[2:3], s[14:15], 0, v[2:3]
	v_add_u32_e32 v150, 0xffffff80, v0
	v_lshl_add_u64 v[164:165], v[150:151], 1, v[2:3]
	s_or_saveexec_b64 s[10:11], s[10:11]
	v_mov_b64_e32 v[166:167], 0x80
	s_xor_b64 exec, exec, s[10:11]
	v_lshlrev_b64 v[2:3], 11, v[2:3]
	v_lshl_add_u64 v[2:3], s[6:7], 0, v[2:3]
	v_ashrrev_i32_e32 v1, 31, v0
	v_lshl_add_u64 v[164:165], v[0:1], 1, v[2:3]
	v_mov_b64_e32 v[166:167], 0x800
	s_or_b64 exec, exec, s[10:11]
	s_add_i32 s64, s64, 2
	v_lshl_or_b32 v0, s64, 6, v144
	v_mul_hi_u32 v2, v0, s36
	v_lshrrev_b32_e32 v150, 2, v2
	v_mad_u64_u32 v[0:1], s[10:11], v150, s35, v[0:1]
	v_lshrrev_b32_e32 v1, 3, v2
	v_bitop3_b32 v0, v0, v1, 7 bitop3:0x78
	v_lshl_add_u64 v[2:3], s[24:25], 0, v[150:151]
	v_cmp_lt_i32_e32 vcc, 15, v0
	v_lshlrev_b32_e32 v0, 3, v0
	s_and_saveexec_b64 s[10:11], vcc
	s_xor_b64 s[10:11], exec, s[10:11]
	v_lshlrev_b64 v[2:3], 7, v[2:3]
	v_lshl_add_u64 v[2:3], s[14:15], 0, v[2:3]
	v_add_u32_e32 v150, 0xffffff80, v0
	v_lshl_add_u64 v[168:169], v[150:151], 1, v[2:3]
	s_or_saveexec_b64 s[10:11], s[10:11]
	s_lshl_b32 s29, s29, 7
	v_mov_b64_e32 v[176:177], 0x80
	s_xor_b64 exec, exec, s[10:11]
	v_lshlrev_b64 v[2:3], 11, v[2:3]
	v_lshl_add_u64 v[2:3], s[6:7], 0, v[2:3]
	v_ashrrev_i32_e32 v1, 31, v0
	v_lshl_add_u64 v[168:169], v[0:1], 1, v[2:3]
	v_mov_b64_e32 v[176:177], 0x800
	s_or_b64 exec, exec, s[10:11]
	v_lshl_or_b32 v2, s56, 7, v144
	s_lshl_b32 s44, s8, 10
	s_or_b32 s54, s44, s29
	v_ashrrev_i32_e32 v0, 3, v2
	v_add_u32_e32 v0, s54, v0
	v_ashrrev_i32_e32 v1, 31, v0
	v_lshlrev_b64 v[64:65], 12, v[0:1]
	v_or_b32_e32 v0, 64, v2
	v_ashrrev_i32_e32 v1, 3, v0
	v_lshrrev_b32_e32 v77, 4, v0
	v_add_u32_e32 v0, s54, v1
	v_xor_b32_e32 v2, v77, v170
	v_ashrrev_i32_e32 v1, 31, v0
	v_lshlrev_b64 v[66:67], 12, v[0:1]
	v_lshlrev_b32_e32 v2, 4, v2
	v_lshl_add_u64 v[0:1], s[42:43], 0, v[66:67]
	v_and_b32_e32 v150, 0x70, v2
	s_sub_i32 s55, 0x4000, s13
	v_lshl_add_u64 v[180:181], v[0:1], 0, v[150:151]
	s_sub_i32 s10, 8, s8
	v_mad_u64_u32 v[0:1], s[8:9], v162, s55, v[160:161]
	s_mul_i32 s9, s56, 0xc00
	s_add_i32 s8, s9, 0
	s_lshl_b32 s13, s57, 10
	s_mov_b32 m0, s8
	s_add_i32 s50, s13, 0
	s_lshl_b32 s57, s64, 10
	s_mov_b32 s11, s17
	global_load_lds_dwordx4 v[0:1], off
	v_mad_u64_u32 v[0:1], s[66:67], v166, s55, v[164:165]
	s_mov_b32 m0, s50
	s_add_i32 s51, s57, 0
	s_lshl_b32 s64, s56, 11
	v_lshl_add_u64 v[178:179], v[152:153], 0, v[64:65]
	global_load_lds_dwordx4 v[0:1], off
	v_mad_u64_u32 v[0:1], s[66:67], v176, s55, v[168:169]
	s_mov_b32 m0, s51
	s_lshl_b64 s[10:11], s[10:11], 22
	s_add_i32 s56, s64, 0
	global_load_lds_dwordx4 v[0:1], off
	s_add_i32 m0, s56, 0x6000
	v_lshl_add_u64 v[0:1], v[178:179], 0, s[10:11]
	global_load_lds_dwordx4 v[0:1], off
	v_lshl_add_u64 v[0:1], v[180:181], 0, s[10:11]
	s_add_i32 m0, s56, 0x6400
	s_lshl_b32 s66, s52, 2
	global_load_lds_dwordx4 v[0:1], off
	s_add_i32 m0, s8, 0xa000
	s_waitcnt vmcnt(0) lgkmcnt(0)
	s_barrier
; #define LAS __attribute__((address_space(3)))
; __device__ __forceinline__ float fexp2(float x) { return __builtin_amdgcn_exp2f(x); }
; __device__ __forceinline__ void attn_unit(LAS unsigned char* lds, const bf16_t* Q, const bf16_t* KN, const bf16_t* KPE, const bf16_t* VT, bf16_t* Y, float* ssq_b, int b, int h, int qg) {
;     ...
;     for (int j = 0; j < ntiles; ++j) {
;         if (j + 1 < ntiles) AT_DMA(j + 1);
;         if (j <= cw) {
;             const LAS unsigned char* kb = lds + (j & 1) * KV_BYTES; const LAS unsigned char* vb = kb + KS_BYTES;
;             f32x16 s0, s1;
; #pragma unroll
;             for (int i = 0; i < 16; ++i) { s0[i] = 0.f; s1[i] = 0.f; }
;             __builtin_amdgcn_s_setprio(1);
;             {
;                 bf16x8 a0n = *(const LAS bf16x8*)(kb + kbase0), a1n = *(const LAS bf16x8*)(kb + (kbase0 + 32u * 384u));
; #pragma unroll
;                 for (int ks = 0; ks < 12; ++ks) {
;                     const bf16x8 a0 = a0n, a1 = a1n;
;                     if (ks + 1 < 12) { const unsigned off = (kbase0 ^ (unsigned)(((2 * (ks + 1)) & 7) << 4)) + (unsigned)(((2 * (ks + 1)) & 24) << 4);
;                         a0n = *(const LAS bf16x8*)(kb + off); a1n = *(const LAS bf16x8*)(kb + (off + 32u * 384u)); }
;                     s0 = __builtin_amdgcn_mfma_f32_32x32x16_bf16(a0, qf[ks], s0, 0, 0, 0);
;                     s1 = __builtin_amdgcn_mfma_f32_32x32x16_bf16(a1, qf[ks], s1, 0, 0, 0);
;                 }
;             }
;             __builtin_amdgcn_s_setprio(0);
;             if (j == 0) {
; #pragma unroll
;                 for (int i = 0; i < 16; ++i) { if (i >= 8) s0[i] = -INFINITY; s1[i] = -INFINITY; }
;             }
;             float mx = s0[0];
; #pragma unroll
;             for (int i = 1; i < 16; ++i) mx = fmaxf(mx, s0[i]);
; #pragma unroll
;             for (int i = 0; i < 16; ++i) mx = fmaxf(mx, s1[i]);
;             mx = fmaxf(mx, __shfl_xor(mx, 32));
;             const bool upd = __builtin_amdgcn_ballot_w64(mx - mrun > 8.0f) != 0ull;
;             const float mn = upd ? fmaxf(mrun, mx) : mrun; const float alpha = upd ? fexp2(mrun - mn) : 1.0f; mrun = mn;
;             s0 = s0 - mn; s1 = s1 - mn;
; #pragma unroll
;             for (int i = 0; i < 16; ++i) { s0[i] = fexp2(s0[i]); s1[i] = fexp2(s1[i]); }
;             const f32x16 t16 = s0 + s1;
;             typedef float f32x8_ __attribute__((ext_vector_type(8)));
	global_load_lds_dwordx4 v[160:161], off
	s_add_i32 m0, s50, 0xa000
	s_lshr_b32 s8, s53, 7
	global_load_lds_dwordx4 v[164:165], off
	s_add_i32 m0, s51, 0xa000
	s_add_i32 s65, s8, s66
	global_load_lds_dwordx4 v[168:169], off
	s_add_i32 m0, s56, 0x10000
	s_add_i32 s65, s65, 1
	global_load_lds_dwordx4 v[178:179], off
	s_add_i32 m0, s56, 0x10400
	s_lshr_b32 s56, s39, 3
	global_load_lds_dwordx4 v[180:181], off
	s_setprio 1
	v_add_u32_e32 v209, 0, v197
	ds_read_b128 v[0:3], v209
	v_add_u32_e32 v210, 0, v199
	ds_read_b128 v[16:19], v210
	v_add_u32_e32 v208, 0, v200
	v_add_u32_e32 v207, 0, v201
	s_waitcnt lgkmcnt(0)
	v_mfma_f32_32x32x16_bf16 v[0:15], v[0:3], v[140:143], 0
	v_mfma_f32_32x32x16_bf16 v[0:15], v[16:19], v[136:139], v[0:15]
	ds_read_b128 v[16:19], v208
	s_waitcnt lgkmcnt(0)
	v_mfma_f32_32x32x16_bf16 v[0:15], v[16:19], v[132:135], v[0:15]
	ds_read_b128 v[16:19], v207
	s_waitcnt lgkmcnt(0)
	v_mfma_f32_32x32x16_bf16 v[0:15], v[16:19], v[128:131], v[0:15]
	ds_read_b128 v[16:19], v209 offset:128
	s_waitcnt lgkmcnt(0)
	v_mfma_f32_32x32x16_bf16 v[0:15], v[16:19], v[124:127], v[0:15]
	ds_read_b128 v[16:19], v210 offset:128
	s_waitcnt lgkmcnt(0)
	v_mfma_f32_32x32x16_bf16 v[0:15], v[16:19], v[120:123], v[0:15]
	ds_read_b128 v[16:19], v208 offset:128
	s_waitcnt lgkmcnt(0)
	v_mfma_f32_32x32x16_bf16 v[0:15], v[16:19], v[116:119], v[0:15]
	ds_read_b128 v[16:19], v207 offset:128
	s_waitcnt lgkmcnt(0)
	v_mfma_f32_32x32x16_bf16 v[0:15], v[16:19], v[112:115], v[0:15]
	ds_read_b128 v[16:19], v209 offset:256
	s_waitcnt lgkmcnt(0)
	v_mfma_f32_32x32x16_bf16 v[0:15], v[16:19], v[108:111], v[0:15]
	ds_read_b128 v[16:19], v210 offset:256
	s_waitcnt lgkmcnt(0)
	v_mfma_f32_32x32x16_bf16 v[0:15], v[16:19], v[104:107], v[0:15]
	ds_read_b128 v[16:19], v208 offset:256
	s_waitcnt lgkmcnt(0)
	v_mfma_f32_32x32x16_bf16 v[0:15], v[16:19], v[100:103], v[0:15]
	ds_read_b128 v[16:19], v207 offset:256
	s_waitcnt lgkmcnt(0)
	v_mfma_f32_32x32x16_bf16 v[0:15], v[16:19], v[96:99], v[0:15]
	s_setprio 0
	s_nop 10
	v_max3_f32 v8, v0, v1, v2
	v_max3_f32 v8, v8, v3, v4
	v_max3_f32 v8, v8, v5, v6
	v_max3_f32 v8, v8, v7, s37
	ds_bpermute_b32 v9, v205, v8
	s_waitcnt lgkmcnt(0)
	v_max_f32_e32 v9, v9, v9
	v_max_f32_e32 v8, v8, v9
	v_add_f32_e32 v9, 0x7f800000, v8
	v_cmp_lt_f32_e32 vcc, s38, v9
	s_cmp_eq_u64 vcc, 0
	v_max_f32_e32 v8, 0xff800000, v8
	s_cselect_b64 vcc, -1, 0
	v_cndmask_b32_e32 v163, v8, v206, vcc
	v_sub_f32_e32 v8, 0xff800000, v163
	v_sub_f32_e32 v7, v7, v163
	v_sub_f32_e32 v6, v6, v163
	v_sub_f32_e32 v5, v5, v163
	v_sub_f32_e32 v4, v4, v163
	v_sub_f32_e32 v3, v3, v163
	v_sub_f32_e32 v2, v2, v163
	v_sub_f32_e32 v1, v1, v163
	v_sub_f32_e32 v0, v0, v163
	v_exp_f32_e32 v76, v8
	v_exp_f32_e32 v16, v0
	v_exp_f32_e32 v17, v1
	v_exp_f32_e32 v18, v2
	v_exp_f32_e32 v19, v3
	v_exp_f32_e32 v20, v6
	v_exp_f32_e32 v21, v7
	v_exp_f32_e32 v22, v4
	v_exp_f32_e32 v23, v5
	v_pk_add_f32 v[0:1], v[76:77], v[18:19] op_sel_hi:[0,1]
	v_pk_add_f32 v[2:3], v[76:77], v[20:21] op_sel_hi:[0,1]
	v_pk_add_f32 v[4:5], v[76:77], v[16:17] op_sel_hi:[0,1]
	v_pk_add_f32 v[6:7], v[76:77], v[22:23] op_sel_hi:[0,1]
	v_pk_fma_f32 v[6:7], v[76:77], 2.0, v[6:7] op_sel_hi:[0,0,1]
	v_pk_fma_f32 v[4:5], v[76:77], 2.0, v[4:5] op_sel_hi:[0,0,1]
	v_pk_fma_f32 v[2:3], v[76:77], 2.0, v[2:3] op_sel_hi:[0,0,1]
	v_pk_fma_f32 v[0:1], v[76:77], 2.0, v[0:1] op_sel_hi:[0,0,1]
	v_pk_add_f32 v[0:1], v[0:1], v[2:3]
	v_pk_add_f32 v[2:3], v[4:5], v[6:7]
	v_cvt_pk_bf16_f32 v68, v16, v17
	v_cvt_pk_bf16_f32 v69, v18, v19
	v_cvt_pk_bf16_f32 v70, v22, v23
	v_cvt_pk_bf16_f32 v71, v20, v21
	s_nop 0
	v_pk_mov_b32 v[4:5], v[2:3], v[0:1] op_sel:[1,0]
	v_mov_b32_e32 v3, v1
	v_pk_add_f32 v[0:1], v[4:5], v[2:3]
	s_nop 0
	v_add_f32_e32 v1, v0, v1
	v_mul_f32_e32 v0, 0, v76
	v_cndmask_b32_e64 v0, v0, 0, vcc
	v_add_f32_e32 v157, v0, v1
	v_mov_b32_e32 v1, v0
	v_mov_b32_e32 v2, v0
	v_mov_b32_e32 v3, v0
	v_mov_b32_e32 v4, v0
	v_mov_b32_e32 v5, v0
	v_mov_b32_e32 v6, v0
	v_mov_b32_e32 v7, v0
	v_mov_b32_e32 v8, v0
	v_mov_b32_e32 v9, v0
	v_mov_b32_e32 v10, v0
	v_mov_b32_e32 v11, v0
	v_mov_b32_e32 v12, v0
	v_mov_b32_e32 v13, v0
	v_mov_b32_e32 v14, v0
	v_mov_b32_e32 v15, v0
	s_setprio 1
	v_add_u32_e32 v215, 0, v198
	ds_read_b128 v[16:19], v215 offset:24576
	ds_read_b128 v[72:75], v215 offset:32768
	s_waitcnt lgkmcnt(0)
	v_mfma_f32_32x32x16_bf16 v[48:63], v[16:19], v[68:71], v[0:15]
	ds_read_b128 v[16:19], v215 offset:28672
	s_waitcnt lgkmcnt(0)
	v_mfma_f32_32x32x16_bf16 v[32:47], v[16:19], v[68:71], v[0:15]
	v_mfma_f32_32x32x16_bf16 v[16:31], v[72:75], v[68:71], v[0:15]
	ds_read_b128 v[72:75], v215 offset:36864
	s_waitcnt lgkmcnt(0)
	v_mfma_f32_32x32x16_bf16 v[0:15], v[72:75], v[68:71], v[0:15]
	s_setprio 0
	v_add_u32_e32 v213, 0, v202
	v_add_u32_e32 v214, 0, v203
	v_add_u32_e32 v216, 0, v204
	v_lshl_add_u64 v[182:183], v[154:155], 0, v[64:65]
	v_bitop3_b32 v64, v77, 7, v170 bitop3:0x48
	v_lshl_or_b32 v66, v64, 4, v66
	v_lshlrev_b32_e32 v150, 6, v176
	v_lshlrev_b32_e32 v188, 6, v166
	v_mov_b32_e32 v189, v151
	v_lshlrev_b32_e32 v192, 6, v162
	v_mov_b32_e32 v193, v151
	v_lshl_add_u64 v[184:185], s[18:19], 0, v[66:67]
	v_lshl_add_u64 v[186:187], v[168:169], 0, v[150:151]
	v_lshl_add_u64 v[190:191], v[164:165], 0, v[188:189]
	v_lshl_add_u64 v[194:195], v[160:161], 0, v[192:193]
	s_mov_b32 s67, -3
	s_waitcnt vmcnt(0)
	s_barrier

; __device__ __forceinline__ int pi32(int r) { return (r & 0x13) | ((r & 4) << 1) | ((r & 8) >> 1); }
; __device__ __forceinline__ void attn_unit(LAS unsigned char* lds, const bf16_t* Q, const bf16_t* KN, const bf16_t* KPE, const bf16_t* VT, bf16_t* Y, float* ssq_b, int b, int h, int qg) {
;     const int tid = threadIdx.x, wid = __builtin_amdgcn_readfirstlane(tid >> 6), lane = tid & 63, q = lane & 31, hh = lane >> 5;
;     const int t0 = 16 + 256 * qg, c0 = 1 + 4 * qg, cw = c0 + (wid >> 1), ntiles = c0 + 4;
;     bf16x8 qf[12];
;     {
;         const bf16_t* qp = Q + (size_t)(b * 2048 + (t0 - 16) + 32 * wid + q) * 1536 + h * 192 + 8 * hh;
; #pragma unroll
;         for (int ks = 0; ks < 12; ++ks) qf[ks] = *(const bf16x8*)(qp + 16 * ks);
;     }
;     f32x16 o[4];
; #pragma unroll
;     for (int d = 0; d < 4; ++d)
; #pragma unroll
;         for (int i = 0; i < 16; ++i) o[d][i] = 0.f;
;     float mrun = -INFINITY, lsum = 0.f;
;     const char* ksrc[3]; unsigned kstr[3]; const char* vsrc[2];
; #pragma unroll
;     for (int i = 0; i < 3; ++i) {
;         const int s = 64 * (wid * 3 + i) + lane; const int key = s / 24, pos = s - key * 24; const int pc = pos ^ ((key >> 1) & 7);
;         const size_t row = (size_t)b * 2048 + key;
;         if (pc < 16) { ksrc[i] = (const char*)(KN + row * 1024 + h * 128 + pc * 8); kstr[i] = 2048u; }
;         else { ksrc[i] = (const char*)(KPE + row * 64 + (pc - 16) * 8); kstr[i] = 128u; }
;     }
; #pragma unroll
;     for (int i = 0; i < 2; ++i) {
;         const int s = 64 * (wid * 2 + i) + lane; const int d = s >> 3, pos = s & 7; const int pc = pos ^ ((d >> 1) & 7);
;         vsrc[i] = (const char*)(VT + ((size_t)((b * 8 + h) * 128 + d)) * 2048 + pc * 8);
;     }
;     ...
;     const int key0 = pi32(q);
;     const unsigned kbase0 = (unsigned)(key0 * 384) + (unsigned)(((hh ^ ((key0 >> 1) & 7))) << 4);
;     const unsigned vbase0 = (unsigned)(q * 128) + (unsigned)((hh ^ ((q >> 1) & 7)) << 4);
;     AT_DMA(0); __syncthreads();
.LBB0_680:
	s_or_b64 exec, exec, s[8:9]
	v_readfirstlane_b32 s52, v170
	s_lshr_b32 s53, s52, 6
	s_lshl_b32 s13, s45, 8
	s_lshl_b32 s28, s53, 5
	v_or_b32_e32 v0, s13, v211
	v_add_u32_e32 v2, s28, v0
	s_waitcnt lgkmcnt(0)
	v_mov_b64_e32 v[0:1], s[60:61]
	v_mad_i64_i32 v[0:1], s[8:9], v2, s31, v[0:1]
	v_lshl_add_u64 v[0:1], v[0:1], 0, s[16:17]
	v_mov_b32_e32 v157, v151
	v_lshl_add_u64 v[0:1], v[0:1], 0, v[156:157]
	global_load_dwordx4 v[140:143], v[0:1], off
	global_load_dwordx4 v[136:139], v[0:1], off offset:32
	global_load_dwordx4 v[132:135], v[0:1], off offset:64
	global_load_dwordx4 v[128:131], v[0:1], off offset:96
	global_load_dwordx4 v[124:127], v[0:1], off offset:128
	global_load_dwordx4 v[120:123], v[0:1], off offset:160
	global_load_dwordx4 v[116:119], v[0:1], off offset:192
	global_load_dwordx4 v[112:115], v[0:1], off offset:224
	global_load_dwordx4 v[108:111], v[0:1], off offset:256
	global_load_dwordx4 v[104:107], v[0:1], off offset:288
	global_load_dwordx4 v[100:103], v[0:1], off offset:320
	global_load_dwordx4 v[96:99], v[0:1], off offset:352
	s_mul_i32 s8, s53, 0xc0
	v_or_b32_e32 v0, s8, v144
	v_mul_hi_u32 v2, v0, s34
	v_lshrrev_b32_e32 v150, 4, v2
	v_mad_u64_u32 v[0:1], s[8:9], v150, s35, v[0:1]
	v_lshrrev_b32_e32 v1, 5, v2
	v_bitop3_b32 v0, v0, v1, 7 bitop3:0x78
	v_lshl_add_u64 v[2:3], s[24:25], 0, v[150:151]
	v_cmp_lt_i32_e32 vcc, 15, v0
	v_lshlrev_b32_e32 v0, 3, v0
	s_and_saveexec_b64 s[8:9], vcc
	s_xor_b64 s[8:9], exec, s[8:9]
	v_lshlrev_b64 v[2:3], 7, v[2:3]
	v_lshl_add_u64 v[2:3], s[14:15], 0, v[2:3]
	v_add_u32_e32 v150, 0xffffff80, v0
	v_lshl_add_u64 v[160:161], v[150:151], 1, v[2:3]
	s_or_saveexec_b64 s[8:9], s[8:9]
	v_mov_b64_e32 v[162:163], 0x80
	s_xor_b64 exec, exec, s[8:9]
	v_lshlrev_b64 v[2:3], 11, v[2:3]
	v_lshl_add_u64 v[2:3], s[6:7], 0, v[2:3]
	v_ashrrev_i32_e32 v1, 31, v0
	v_lshl_add_u64 v[160:161], v[0:1], 1, v[2:3]
	v_mov_b64_e32 v[162:163], 0x800
	s_or_b64 exec, exec, s[8:9]
	s_mul_i32 s57, s53, 3
	s_add_i32 s16, s57, 1
	v_lshl_or_b32 v0, s16, 6, v144
	v_mul_hi_u32 v2, v0, s36
	v_lshrrev_b32_e32 v150, 2, v2
	v_mad_u64_u32 v[0:1], s[8:9], v150, s35, v[0:1]
	v_lshrrev_b32_e32 v1, 3, v2
	v_bitop3_b32 v0, v0, v1, 7 bitop3:0x78
	v_lshl_add_u64 v[2:3], s[24:25], 0, v[150:151]
	v_cmp_lt_i32_e32 vcc, 15, v0
	v_lshlrev_b32_e32 v0, 3, v0
	s_and_saveexec_b64 s[8:9], vcc
	s_xor_b64 s[8:9], exec, s[8:9]
	v_lshlrev_b64 v[2:3], 7, v[2:3]
	v_lshl_add_u64 v[2:3], s[14:15], 0, v[2:3]
	v_add_u32_e32 v150, 0xffffff80, v0
	v_lshl_add_u64 v[164:165], v[150:151], 1, v[2:3]
	s_or_saveexec_b64 s[8:9], s[8:9]
	v_mov_b64_e32 v[166:167], 0x80
	s_xor_b64 exec, exec, s[8:9]
	v_lshlrev_b64 v[2:3], 11, v[2:3]
	v_lshl_add_u64 v[2:3], s[6:7], 0, v[2:3]
	v_ashrrev_i32_e32 v1, 31, v0
	v_lshl_add_u64 v[164:165], v[0:1], 1, v[2:3]
	v_mov_b64_e32 v[166:167], 0x800
	s_or_b64 exec, exec, s[8:9]
	s_add_i32 s57, s57, 2
	v_lshl_or_b32 v0, s57, 6, v144
	v_mul_hi_u32 v2, v0, s36
	v_lshrrev_b32_e32 v150, 2, v2
	v_mad_u64_u32 v[0:1], s[8:9], v150, s35, v[0:1]
	v_lshrrev_b32_e32 v1, 3, v2
	v_bitop3_b32 v0, v0, v1, 7 bitop3:0x78
	v_lshl_add_u64 v[2:3], s[24:25], 0, v[150:151]
	v_cmp_lt_i32_e32 vcc, 15, v0
	v_lshlrev_b32_e32 v0, 3, v0
	s_and_saveexec_b64 s[8:9], vcc
	s_xor_b64 s[8:9], exec, s[8:9]
	v_lshlrev_b64 v[2:3], 7, v[2:3]
	v_lshl_add_u64 v[2:3], s[14:15], 0, v[2:3]
	v_add_u32_e32 v150, 0xffffff80, v0
	v_lshl_add_u64 v[168:169], v[150:151], 1, v[2:3]
	s_or_saveexec_b64 s[8:9], s[8:9]
	v_mov_b64_e32 v[176:177], 0x80
	s_xor_b64 exec, exec, s[8:9]
	v_lshlrev_b64 v[2:3], 11, v[2:3]
	v_lshl_add_u64 v[2:3], s[6:7], 0, v[2:3]
	v_ashrrev_i32_e32 v1, 31, v0
	v_lshl_add_u64 v[168:169], v[0:1], 1, v[2:3]
	v_mov_b64_e32 v[176:177], 0x800
	s_or_b64 exec, exec, s[8:9]
	v_lshl_or_b32 v2, s53, 7, v144
	v_ashrrev_i32_e32 v73, 3, v2
	v_add_u32_e32 v0, s54, v73
	v_ashrrev_i32_e32 v1, 31, v0
	v_lshlrev_b64 v[0:1], 12, v[0:1]
	v_lshl_add_u64 v[178:179], v[152:153], 0, v[0:1]
	v_or_b32_e32 v0, 64, v2
	v_ashrrev_i32_e32 v74, 3, v0
	v_lshrrev_b32_e32 v75, 4, v0
	v_add_u32_e32 v0, s54, v74
	v_xor_b32_e32 v2, v75, v170
	v_ashrrev_i32_e32 v1, 31, v0
	v_lshlrev_b64 v[0:1], 12, v[0:1]
	v_lshlrev_b32_e32 v2, 4, v2
	v_lshl_add_u64 v[0:1], s[42:43], 0, v[0:1]
	v_and_b32_e32 v150, 0x70, v2
	v_lshl_add_u64 v[180:181], v[0:1], 0, v[150:151]
	v_mad_u64_u32 v[0:1], s[6:7], v162, s55, v[160:161]
	s_mul_i32 s7, s53, 0xc00
	s_add_i32 s6, s7, 0
	s_mov_b32 m0, s6
	s_nop 0
	global_load_lds_dwordx4 v[0:1], off
	v_mad_u64_u32 v[0:1], s[8:9], v166, s55, v[164:165]
	s_lshl_b32 s8, s16, 10
	s_add_i32 s16, s8, 0
	s_mov_b32 m0, s16
	s_lshl_b32 s9, s57, 10
	global_load_lds_dwordx4 v[0:1], off
	v_mad_u64_u32 v[0:1], s[54:55], v176, s55, v[168:169]
	s_add_i32 s50, s9, 0
	s_lshl_b32 s54, s53, 11
	s_mov_b32 m0, s50
	s_add_i32 s51, s54, 0
	global_load_lds_dwordx4 v[0:1], off
	s_add_i32 m0, s51, 0x6000
	v_lshl_add_u64 v[0:1], v[178:179], 0, s[10:11]
	global_load_lds_dwordx4 v[0:1], off
	v_lshl_add_u64 v[0:1], v[180:181], 0, s[10:11]
	s_add_i32 m0, s51, 0x6400
	s_lshl_b32 s11, s45, 2
	global_load_lds_dwordx4 v[0:1], off
	s_add_i32 m0, s6, 0xa000
	s_waitcnt vmcnt(0) lgkmcnt(0)
	s_barrier
; __device__ __forceinline__ void attn_unit(LAS unsigned char* lds, const bf16_t* Q, const bf16_t* KN, const bf16_t* KPE, const bf16_t* VT, bf16_t* Y, float* ssq_b, int b, int h, int qg) {
;     ...
;         if (j + 1 < ntiles) AT_DMA(j + 1);
;         if (j <= cw) {
;             const LAS unsigned char* kb = lds + (j & 1) * KV_BYTES; const LAS unsigned char* vb = kb + KS_BYTES;
;             f32x16 s0, s1;
; #pragma unroll
;             for (int i = 0; i < 16; ++i) { s0[i] = 0.f; s1[i] = 0.f; }
;             __builtin_amdgcn_s_setprio(1);
;             {
;                 bf16x8 a0n = *(const LAS bf16x8*)(kb + kbase0), a1n = *(const LAS bf16x8*)(kb + (kbase0 + 32u * 384u));
; #pragma unroll
;                 for (int ks = 0; ks < 12; ++ks) {
;                     const bf16x8 a0 = a0n, a1 = a1n;
;                     if (ks + 1 < 12) { const unsigned off = (kbase0 ^ (unsigned)(((2 * (ks + 1)) & 7) << 4)) + (unsigned)(((2 * (ks + 1)) & 24) << 4);
;                         a0n = *(const LAS bf16x8*)(kb + off); a1n = *(const LAS bf16x8*)(kb + (off + 32u * 384u)); }
;                     s0 = __builtin_amdgcn_mfma_f32_32x32x16_bf16(a0, qf[ks], s0, 0, 0, 0);
;                     s1 = __builtin_amdgcn_mfma_f32_32x32x16_bf16(a1, qf[ks], s1, 0, 0, 0);
;                 }
;             }
;             __builtin_amdgcn_s_setprio(0);
;             if (j == 0) {
; #pragma unroll
;                 for (int i = 0; i < 16; ++i) { if (i >= 8) s0[i] = -INFINITY; s1[i] = -INFINITY; }
;             }
;             float mx = s0[0];
; #pragma unroll
;             for (int i = 1; i < 16; ++i) mx = fmaxf(mx, s0[i]);
; #pragma unroll
;             for (int i = 0; i < 16; ++i) mx = fmaxf(mx, s1[i]);
;             mx = fmaxf(mx, __shfl_xor(mx, 32));
;             const bool upd = __builtin_amdgcn_ballot_w64(mx - mrun > 8.0f) != 0ull;
;             const float mn = upd ? fmaxf(mrun, mx) : mrun; const float alpha = upd ? fexp2(mrun - mn) : 1.0f; mrun = mn;
;             s0 = s0 - mn; s1 = s1 - mn;
; #pragma unroll
;             for (int i = 0; i < 16; ++i) { s0[i] = fexp2(s0[i]); s1[i] = fexp2(s1[i]); }
;             const f32x16 t16 = s0 + s1;
;             typedef float f32x8_ __attribute__((ext_vector_type(8)));
;             const f32x8_ t8 = __builtin_shufflevector(t16, t16, 0, 1, 2, 3, 4, 5, 6, 7) + __builtin_shufflevector(t16, t16, 8, 9, 10, 11, 12, 13, 14, 15);
	global_load_lds_dwordx4 v[160:161], off
	s_add_i32 m0, s16, 0xa000
	s_lshr_b32 s6, s52, 7
	global_load_lds_dwordx4 v[164:165], off
	s_add_i32 m0, s50, 0xa000
	s_add_i32 s10, s6, s11
	global_load_lds_dwordx4 v[168:169], off
	s_add_i32 m0, s51, 0x10000
	s_and_b32 s6, s56, 3
	global_load_lds_dwordx4 v[178:179], off
	s_add_i32 m0, s51, 0x10400
	s_add_i32 s10, s10, 1
	global_load_lds_dwordx4 v[180:181], off
	s_lshl_b32 s16, s6, 2
	s_setprio 1
	ds_read_b128 v[0:3], v209
	ds_read_b128 v[16:19], v210
	s_waitcnt lgkmcnt(0)
	v_mfma_f32_32x32x16_bf16 v[0:15], v[0:3], v[140:143], 0
	v_mfma_f32_32x32x16_bf16 v[0:15], v[16:19], v[136:139], v[0:15]
	ds_read_b128 v[16:19], v208
	s_waitcnt lgkmcnt(0)
	v_mfma_f32_32x32x16_bf16 v[0:15], v[16:19], v[132:135], v[0:15]
	ds_read_b128 v[16:19], v207
	s_waitcnt lgkmcnt(0)
	v_mfma_f32_32x32x16_bf16 v[0:15], v[16:19], v[128:131], v[0:15]
	ds_read_b128 v[16:19], v209 offset:128
	s_waitcnt lgkmcnt(0)
	v_mfma_f32_32x32x16_bf16 v[0:15], v[16:19], v[124:127], v[0:15]
	ds_read_b128 v[16:19], v210 offset:128
	s_waitcnt lgkmcnt(0)
	v_mfma_f32_32x32x16_bf16 v[0:15], v[16:19], v[120:123], v[0:15]
	ds_read_b128 v[16:19], v208 offset:128
	s_waitcnt lgkmcnt(0)
	v_mfma_f32_32x32x16_bf16 v[0:15], v[16:19], v[116:119], v[0:15]
	ds_read_b128 v[16:19], v207 offset:128
	s_waitcnt lgkmcnt(0)
	v_mfma_f32_32x32x16_bf16 v[0:15], v[16:19], v[112:115], v[0:15]
	ds_read_b128 v[16:19], v209 offset:256
	s_waitcnt lgkmcnt(0)
	v_mfma_f32_32x32x16_bf16 v[0:15], v[16:19], v[108:111], v[0:15]
	ds_read_b128 v[16:19], v210 offset:256
	s_waitcnt lgkmcnt(0)
	v_mfma_f32_32x32x16_bf16 v[0:15], v[16:19], v[104:107], v[0:15]
	ds_read_b128 v[16:19], v208 offset:256
	s_waitcnt lgkmcnt(0)
	v_mfma_f32_32x32x16_bf16 v[0:15], v[16:19], v[100:103], v[0:15]
	ds_read_b128 v[16:19], v207 offset:256
	s_waitcnt lgkmcnt(0)
	v_mfma_f32_32x32x16_bf16 v[0:15], v[16:19], v[96:99], v[0:15]
	s_setprio 0
	s_nop 10
	v_max3_f32 v8, v0, v1, v2
	v_max3_f32 v8, v8, v3, v4
	v_max3_f32 v8, v8, v5, v6
	v_max3_f32 v8, v8, v7, s37
	ds_bpermute_b32 v9, v205, v8
	s_waitcnt lgkmcnt(0)
	v_max_f32_e32 v9, v9, v9
	v_max_f32_e32 v8, v8, v9
	v_add_f32_e32 v9, 0x7f800000, v8
	v_cmp_lt_f32_e32 vcc, s38, v9
	s_cmp_eq_u64 vcc, 0
	v_max_f32_e32 v8, 0xff800000, v8
	s_cselect_b64 vcc, -1, 0
	v_cndmask_b32_e32 v163, v8, v206, vcc
	v_sub_f32_e32 v8, 0xff800000, v163
	v_sub_f32_e32 v7, v7, v163
	v_sub_f32_e32 v6, v6, v163
	v_sub_f32_e32 v5, v5, v163
	v_sub_f32_e32 v4, v4, v163
	v_sub_f32_e32 v3, v3, v163
	v_sub_f32_e32 v2, v2, v163
	v_sub_f32_e32 v1, v1, v163
	v_sub_f32_e32 v0, v0, v163
	v_exp_f32_e32 v72, v8
	v_exp_f32_e32 v16, v0
	v_exp_f32_e32 v17, v1
	v_exp_f32_e32 v18, v2
	v_exp_f32_e32 v19, v3
	v_exp_f32_e32 v20, v6
	v_exp_f32_e32 v21, v7
	v_exp_f32_e32 v22, v4
	v_exp_f32_e32 v23, v5
	v_pk_add_f32 v[0:1], v[72:73], v[18:19] op_sel_hi:[0,1]
	v_pk_add_f32 v[2:3], v[72:73], v[20:21] op_sel_hi:[0,1]
	v_pk_add_f32 v[4:5], v[72:73], v[16:17] op_sel_hi:[0,1]
	v_pk_add_f32 v[6:7], v[72:73], v[22:23] op_sel_hi:[0,1]
	v_pk_fma_f32 v[6:7], v[72:73], 2.0, v[6:7] op_sel_hi:[0,0,1]
	v_pk_fma_f32 v[4:5], v[72:73], 2.0, v[4:5] op_sel_hi:[0,0,1]
	v_pk_fma_f32 v[2:3], v[72:73], 2.0, v[2:3] op_sel_hi:[0,0,1]
	v_pk_fma_f32 v[0:1], v[72:73], 2.0, v[0:1] op_sel_hi:[0,0,1]
	v_pk_add_f32 v[0:1], v[0:1], v[2:3]
	v_pk_add_f32 v[2:3], v[4:5], v[6:7]
	v_cvt_pk_bf16_f32 v64, v16, v17
	v_cvt_pk_bf16_f32 v65, v18, v19
	v_cvt_pk_bf16_f32 v66, v22, v23
	v_cvt_pk_bf16_f32 v67, v20, v21
	s_nop 0
	v_pk_mov_b32 v[4:5], v[2:3], v[0:1] op_sel:[1,0]
	v_mov_b32_e32 v3, v1
	v_pk_add_f32 v[0:1], v[4:5], v[2:3]
	s_nop 0
	v_add_f32_e32 v1, v0, v1
	v_mul_f32_e32 v0, 0, v72
	v_cndmask_b32_e64 v0, v0, 0, vcc
	v_add_f32_e32 v157, v0, v1
	v_mov_b32_e32 v1, v0
	v_mov_b32_e32 v2, v0
	v_mov_b32_e32 v3, v0
	v_mov_b32_e32 v4, v0
	v_mov_b32_e32 v5, v0
	v_mov_b32_e32 v6, v0
	v_mov_b32_e32 v7, v0
	v_mov_b32_e32 v8, v0
	v_mov_b32_e32 v9, v0
	v_mov_b32_e32 v10, v0
	v_mov_b32_e32 v11, v0
	v_mov_b32_e32 v12, v0
	v_mov_b32_e32 v13, v0
	v_mov_b32_e32 v14, v0
	v_mov_b32_e32 v15, v0
	s_setprio 1
	ds_read_b128 v[16:19], v215 offset:24576
	ds_read_b128 v[68:71], v215 offset:32768
	s_waitcnt lgkmcnt(0)
	v_mfma_f32_32x32x16_bf16 v[48:63], v[16:19], v[64:67], v[0:15]
	ds_read_b128 v[16:19], v215 offset:28672
	s_waitcnt lgkmcnt(0)
	v_mfma_f32_32x32x16_bf16 v[32:47], v[16:19], v[64:67], v[0:15]
	v_mfma_f32_32x32x16_bf16 v[16:31], v[68:71], v[64:67], v[0:15]
	ds_read_b128 v[68:71], v215 offset:36864
	s_waitcnt lgkmcnt(0)
	v_mfma_f32_32x32x16_bf16 v[0:15], v[68:71], v[64:67], v[0:15]
	s_setprio 0
	s_add_i32 s29, s29, s44
	v_add_u32_e32 v64, s29, v73
	v_ashrrev_i32_e32 v65, 31, v64
	v_lshlrev_b64 v[64:65], 12, v[64:65]
	v_lshl_add_u64 v[182:183], v[154:155], 0, v[64:65]
	v_add_u32_e32 v64, s29, v74
	v_ashrrev_i32_e32 v65, 31, v64
	v_lshlrev_b64 v[64:65], 12, v[64:65]
	v_bitop3_b32 v66, v75, 7, v170 bitop3:0x48
	v_lshl_or_b32 v64, v66, 4, v64
	v_lshlrev_b32_e32 v150, 6, v176
	v_lshlrev_b32_e32 v188, 6, v166
	v_mov_b32_e32 v189, v151
	v_lshlrev_b32_e32 v192, 6, v162
	v_mov_b32_e32 v193, v151
	v_lshl_add_u64 v[184:185], s[18:19], 0, v[64:65]
	v_lshl_add_u64 v[186:187], v[168:169], 0, v[150:151]
	v_lshl_add_u64 v[190:191], v[164:165], 0, v[188:189]
	v_lshl_add_u64 v[194:195], v[160:161], 0, v[192:193]
	s_mov_b32 s29, -3
	s_waitcnt vmcnt(0)
	s_barrier
